# M1 pool pairs of the three-unit groups (A,B) executed by the two-unit groups (D,C)
# baseline (speedup 1.0000x reference)
.LBB0_363:
	s_lshl_b32 s10, s26, 14
	v_readlane_b32 s11, v252, 6
	v_readlane_b32 s74, v252, 5
	v_readlane_b32 s75, v255, 62
	s_nop 3
	s_mov_b32 s90, -1
	s_lshr_b32 s91, s74, 6
	s_and_b32 s74, s74, 7
	s_lshl_b32 s74, s74, 5
	s_cmp_lg_u32 s75, 0
	s_cselect_b32 s74, s74, 0
	s_add_i32 s11, s11, s74
	s_cmp_eq_u32 s75, 0
	s_cbranch_scc1 .LBB0_365
	s_cmp_lt_u32 s91, 2
	s_cbranch_scc1 .LBB0_397
	s_cmp_eq_u32 s91, 2
	s_cselect_b32 s90, 8, 24
	s_sub_i32 s90, s11, s90
	s_branch .LBB0_365
.LBB0_364:
	s_cmp_lt_i32 s90, 0
	s_cbranch_scc1 .Lpool_latch
	s_mov_b32 s11, s90
	s_mov_b32 s90, -1
	s_branch .LBB0_365
